# late weight-conversion (live copy): tile index decomposition swapped so consecutive waves read adjacent 256B column blocks of the same rows
# speedup vs baseline: 1.0236x; 1.0001x over previous
.LBB0_1014:
	s_abs_i32 s6, s66
	s_mul_hi_u32 s7, s6, s65
	s_mul_i32 s7, s7, s33
	s_lshr_b32 s70, s68, 6
	s_sub_i32 s6, s6, s7
	s_mul_i32 s69, s70, s4
	s_mov_b32 s99, s4
	s_ashr_i32 s4, s66, 31
	s_sub_i32 s7, s6, s33
	s_cmp_ge_u32 s6, s33
	s_cselect_b32 s6, s7, s6
	s_sub_i32 s7, s6, s33
	s_cmp_ge_u32 s6, s33
	s_cselect_b32 s6, s7, s6
	s_xor_b32 s6, s6, s4
	s_sub_i32 s4, s4, s6
	v_add_u32_e32 v2, s4, v76
	v_sub_u32_e32 v3, 0, v2
	v_ashrrev_i32_e32 v0, 31, v2
	v_max_i32_e32 v2, v2, v3
	v_mul_hi_u32 v3, v2, s65
	v_mul_lo_u32 v3, v3, s33
	v_sub_u32_e32 v2, v2, v3
	v_subrev_u32_e32 v3, s33, v2
	v_cmp_le_u32_e32 vcc, s33, v2
	s_nop 1
	v_cndmask_b32_e32 v2, v2, v3, vcc
	v_subrev_u32_e32 v3, s33, v2
	v_cmp_le_u32_e32 vcc, s33, v2
	s_nop 1
	v_cndmask_b32_e32 v2, v2, v3, vcc
	v_xor_b32_e32 v4, v2, v0
	v_sub_u32_e32 v77, v4, v0
	v_cmp_gt_i32_e32 vcc, s69, v77
	s_and_saveexec_b64 s[6:7], vcc
	s_cbranch_execz .LBB0_974
	v_sub_co_u32_e64 v2, s[8:9], s67, 4
	s_xor_b64 s[8:9], s[8:9], -1
	s_cmp_gt_u32 s67, 7
	v_cvt_f32_u32_e32 v6, s99
	s_cselect_b64 s[10:11], -1, 0
	s_add_i32 s4, s67, -13
	s_lshr_b32 s21, s67, 1
	s_lshl_b64 s[14:15], s[4:5], 21
	s_and_b32 s4, s67, 1
	s_lshl_b32 s20, s21, 10
	s_lshl_b64 s[12:13], s[12:13], 1
	s_add_u32 s12, s18, s12
	v_readlane_b32 s36, v253, 18
	s_addc_u32 s13, s19, s13
	v_readlane_b32 s44, v253, 26
	v_rcp_iflag_f32_e32 v6, v6
	v_readlane_b32 s40, v253, 22
	v_readlane_b32 s41, v253, 23
	v_readlane_b32 s42, v253, 24
	v_readlane_b32 s43, v253, 25
	v_readlane_b32 s45, v253, 27
	v_readlane_b32 s46, v253, 28
	v_readlane_b32 s47, v253, 29
	v_readlane_b32 s48, v253, 30
	v_readlane_b32 s49, v253, 31
	v_readlane_b32 s50, v253, 32
	v_readlane_b32 s51, v253, 33
	s_add_u32 s14, s44, s14
	s_addc_u32 s15, s45, s15
	v_readlane_b32 s40, v253, 2
	v_readlane_b32 s41, v253, 3
	v_readlane_b32 s42, v253, 4
	v_readlane_b32 s43, v253, 5
	v_readlane_b32 s44, v253, 6
	v_readlane_b32 s45, v253, 7
	v_readlane_b32 s46, v253, 8
	v_readlane_b32 s47, v253, 9
	v_readlane_b32 s48, v253, 10
	v_readlane_b32 s49, v253, 11
	v_readlane_b32 s50, v253, 12
	v_readlane_b32 s51, v253, 13
	v_readlane_b32 s52, v253, 14
	v_readlane_b32 s53, v253, 15
	v_readlane_b32 s54, v253, 16
	v_readlane_b32 s55, v253, 17
	s_mov_b64 s[40:41], s[44:45]
	v_mul_f32_e32 v6, 0x4f7ffffe, v6
	v_readlane_b32 s37, v253, 19
	v_readlane_b32 s38, v253, 20
	v_readlane_b32 s39, v253, 21
	s_cmp_eq_u32 s4, 0
	s_mul_i32 s4, s21, 0xb00000
	s_mov_b32 s21, s5
	s_mov_b64 s[42:43], s[46:47]
	s_mov_b64 s[44:45], s[48:49]
	s_mov_b64 s[46:47], s[50:51]
	s_mov_b64 s[48:49], s[52:53]
	s_mov_b64 s[50:51], s[54:55]
	v_cvt_u32_f32_e32 v6, v6
	s_cselect_b32 s23, s47, s39
	s_cselect_b32 s22, s46, s38
	s_cselect_b32 s71, s43, s51
	s_cselect_b32 s26, s42, s50
	s_cselect_b32 s27, s45, s37
	s_cselect_b32 s28, s44, s36
	s_cselect_b32 s24, s41, s49
	s_cselect_b32 s25, s40, s48
	s_lshl_b64 s[20:21], s[20:21], 2
	s_add_u32 s34, s25, s20
	s_addc_u32 s35, s24, s21
	s_sub_i32 s20, 0, s99
	v_lshrrev_b32_e32 v2, 1, v2
	v_mul_lo_u32 v7, s20, v6
	v_mul_hi_u32 v3, v2, s64
	v_mul_lo_u32 v2, v2, s64
	v_mul_hi_u32 v7, v6, v7
	s_lshl_b32 s20, s99, 6
	v_lshlrev_b32_e32 v4, 6, v4
	v_lshlrev_b32_e32 v0, 6, v0
	v_lshl_add_u64 v[2:3], s[22:23], 0, v[2:3]
	v_add_u32_e32 v78, v6, v7
	s_sub_i32 s22, 0, s20
	v_sub_u32_e32 v4, v4, v0
	s_mov_b64 s[36:37], 0
	s_branch .LBB0_1017

.LBB0_1017:
	v_sub_u32_e32 v6, 0, v77
	v_max_i32_e32 v6, v77, v6
	v_mul_hi_u32 v7, v6, v78
	v_mul_lo_u32 v8, v7, s99
	v_sub_u32_e32 v6, v6, v8
	v_add_u32_e32 v8, 1, v7
	v_cmp_le_u32_e32 vcc, s99, v6
	v_ashrrev_i32_e32 v0, 31, v77
	s_nop 0
	v_cndmask_b32_e32 v7, v7, v8, vcc
	v_subrev_u32_e32 v8, s99, v6
	v_cndmask_b32_e32 v6, v6, v8, vcc
	v_add_u32_e32 v8, 1, v7
	v_cmp_le_u32_e32 vcc, s99, v6
	s_nop 1
	v_cndmask_b32_e32 v6, v7, v8, vcc
	v_xor_b32_e32 v6, v6, v0
	v_sub_u32_e32 v8, v6, v0
	v_lshlrev_b32_e32 v200, 6, v8
	v_mul_lo_u32 v9, v8, s22
	v_add_u32_e32 v9, v9, v4
	v_ashrrev_i32_e32 v8, 6, v9
	v_or_b32_e32 v6, v9, v178
	s_and_b64 vcc, exec, s[8:9]
	s_cbranch_vccz .LBB0_1023
	s_and_b64 vcc, exec, s[10:11]
	s_cbranch_vccz .LBB0_1024
	s_cmp_lt_i32 s67, 11
	s_mov_b64 s[56:57], 0
	s_cbranch_scc1 .LBB0_1025
	s_cmp_gt_i32 s67, 11
	s_cbranch_scc0 .LBB0_1028
	s_cmp_eq_u32 s67, 12
	s_cbranch_scc0 .LBB0_1172
	v_lshlrev_b32_e32 v0, 1, v6
	v_lshrrev_b32_e32 v7, 2, v9
	v_and_b32_e32 v0, 0xc0, v0
	v_and_b32_e32 v7, 32, v7
	v_and_b32_e32 v10, 0xffffff1f, v6
	s_movk_i32 s20, 0x300
	v_or3_b32 v0, v7, v10, v0
	v_cmp_gt_i32_e32 vcc, s20, v6
	v_readlane_b32 s40, v253, 40
	v_readlane_b32 s54, v253, 54
	v_cndmask_b32_e32 v10, v6, v0, vcc
	v_ashrrev_i32_e32 v11, 31, v10
	v_readlane_b32 s55, v253, 55
	v_lshl_add_u64 v[20:21], v[10:11], 2, s[72:73]
	s_mov_b64 s[58:59], 0
	s_mov_b64 s[38:39], s[54:55]
	v_readlane_b32 s41, v253, 41
	v_readlane_b32 s42, v253, 42
	v_readlane_b32 s43, v253, 43
	v_readlane_b32 s44, v253, 44
	v_readlane_b32 s45, v253, 45
	v_readlane_b32 s46, v253, 46
	v_readlane_b32 s47, v253, 47
	v_readlane_b32 s48, v253, 48
	v_readlane_b32 s49, v253, 49
	v_readlane_b32 s50, v253, 50
	v_readlane_b32 s51, v253, 51
	v_readlane_b32 s52, v253, 52
	v_readlane_b32 s53, v253, 53
	s_mov_b64 s[42:43], 0x600
	s_branch .LBB0_1030

.LBB0_1042:
	v_mov_b32_e32 v8, v200
	v_cmp_ne_u64_e32 vcc, 0, v[20:21]
	v_mov_b32_e32 v11, 0
	v_ashrrev_i32_e32 v9, 31, v8
	v_mov_b32_e32 v10, 0
	s_and_saveexec_b64 s[56:57], vcc
	s_cbranch_execz .LBB0_1044
	v_mul_lo_u32 v0, s43, v8
	v_mul_lo_u32 v7, s42, v9
	v_mad_u64_u32 v[12:13], s[20:21], s42, v8, 0
	v_add3_u32 v13, v13, v7, v0
	v_lshl_add_u64 v[12:13], v[12:13], 2, v[20:21]
	global_load_dword v10, v[12:13], off
